# P4 sample up-projection epilogue: same LDS staging of the row sum-of-squares partials as P6
# baseline (speedup 1.0000x reference)
; DI int tid_of(int wave0) { int t = wave0 * 64 + lane_id(); asm volatile("" : "+v"(t)); return t; }
; #define PG8_BAR __builtin_amdgcn_s_barrier()
;     __device__ __forceinline__ void operator()(const f32x4 (&acc)[2][2][4][2], const Unit& u, int wr, int wc, int fr, int fq) const {
;         float rsv[8];
; #pragma unroll
;         for (int idx = 0; idx < 8; ++idx) { const f32x4 q = *(const f32x4*)(rowss + (size_t)(u.pm * BM + (idx >> 2) * HALF + wr * 64 + (idx & 3) * 16 + fr) * 4); rsv[idx] = (q[0] + q[1]) + (q[2] + q[3]); }
;     const int tid = tid_of(wave0), wid = wave0, lane = tid & 63, wr = wid >> 2, wc = wid & 3, fr = lane & 15, fq = lane >> 4;
;     const int K = g.K;
;     unsigned voffA[2], voffB[2];
; #pragma unroll
;     for (int i = 0; i < 2; ++i) { int R, C; stage_rc(tid * 16 + i * 8192, R, C); const int Rb = (R >> 5) * 64 + (Epi::PERM ? perm32(R & 31) : (R & 31));
;         voffA[i] = (unsigned)(R * K + C) * 2u; voffB[i] = (unsigned)(Rb * K + C) * 2u; }
;     const size_t kstep = (size_t)(BK * 2);
;     const size_t hstep = (size_t)HALF * K * 2;
;     const size_t tstep = 2 * hstep;
;     const size_t hstepB = (size_t)32 * K * 2;
;     const unsigned ldsw = (unsigned)wid * 1024u;
;     const int aoff = lds_byte(wr * 64 + fr, fq * 8), boff = lds_byte(wc * 32 + fr, fq * 8);
;     ...
;     Unit cur, nxt; int ui = 0;
;     if (!S.next(0, cur)) return;
;     f32x4 acc[2][2][4][2];
; #pragma unroll
;     for (int a = 0; a < 2; ++a)
; #pragma unroll
;         for (int b = 0; b < 2; ++b)
; #pragma unroll
;             for (int m = 0; m < 4; ++m)
; #pragma unroll
;                 for (int n = 0; n < 2; ++n) acc[a][b][m][n] = (f32x4){0.f, 0.f, 0.f, 0.f};
;     bf16x8 At[4][2], B0[2][2], B1[2][2];
;     const char* cA = (const char*)g.A + (size_t)cur.pm * tstep + (size_t)cur.k0 * (BK * 2); const char* cB = (const char*)g.Bt + (size_t)cur.pn * tstep + (size_t)cur.k0 * (BK * 2);
;     S.a_ready(cur);
;     if constexpr (SP2) {
;         PG8_STAGE(PG8_SB(0, 0), cB, voffB); PG8_STAGE(PG8_SB(0, 1), cB + hstepB, voffB); PG8_STAGEA(PG8_SA(0, 0), cA, voffA); PG8_STAGEA(PG8_SA(0, 1), cA + hstep, voffA);
;         if (wr == 1) PG8_BAR;
;         PG8_WAIT_V(2); PG8_BAR;
;         PG8_STAGE(PG8_SB(1, 0), cB + kstep, voffB); PG8_STAGEA(PG8_SA(1, 0), cA + kstep, voffA); PG8_STAGE(PG8_SB(1, 1), cB + hstepB + kstep, voffB);
;         PG8_WAIT_V(6); PG8_BAR;
.LBB0_754:
	s_andn2_b64 vcc, exec, s[0:1]
	s_cbranch_vccnz .LBB0_786
	v_mov_b32_e32 v11, v175
	s_ashr_i32 s0, s2, 31
	v_lshlrev_b32_e32 v0, 4, v11
	v_add_u32_e32 v1, 0x2000, v0
	v_ashrrev_i32_e32 v2, 31, v1
	v_lshrrev_b32_e32 v2, 22, v2
	v_add_u32_e32 v2, v1, v2
	v_ashrrev_i32_e32 v8, 10, v2
	v_mul_i32_i24_e32 v2, 0x400, v8
	v_sub_u32_e32 v1, v1, v2
	v_lshrrev_b32_e32 v2, 4, v1
	v_bitop3_b32 v1, v2, v1, 32 bitop3:0x6c
	v_ashrrev_i32_e32 v2, 31, v1
	v_lshrrev_b32_e32 v2, 26, v2
	v_add_u32_e32 v2, v1, v2
	v_lshlrev_b32_e32 v3, 3, v8
	v_ashrrev_i32_e32 v9, 6, v2
	v_and_b32_e32 v3, -16, v3
	v_add_u32_e32 v3, v9, v3
	v_lshrrev_b32_e32 v4, 2, v3
	v_lshlrev_b32_e32 v6, 1, v3
	v_and_b32_e32 v2, 0xc0, v2
	v_and_b32_e32 v4, 4, v4
	v_and_b32_e32 v5, 3, v9
	v_and_b32_e32 v6, 0x1fffd8, v6
	v_sub_u32_e32 v1, v1, v2
	v_mov_b32_e32 v2, 1
	v_or3_b32 v4, v5, v4, v6
	v_lshlrev_b32_e32 v5, 5, v8
	v_ashrrev_i16_sdwa v1, v2, sext(v1) dst_sel:DWORD dst_unused:UNUSED_PAD src0_sel:DWORD src1_sel:BYTE_0
	v_and_b32_e32 v5, 32, v5
	v_bfe_i32 v10, v1, 0, 16
	v_add_lshl_u32 v1, v5, v10, 1
	v_lshl_add_u32 v130, v4, 11, v1
	v_lshl_add_u32 v132, v3, 11, v1
	v_bfe_i32 v1, v11, 27, 1
	v_lshrrev_b32_e32 v1, 22, v1
	v_add_u32_e32 v1, v0, v1
	v_and_b32_e32 v1, 0xfffffc00, v1
	v_sub_u32_e32 v0, v0, v1
	v_lshrrev_b32_e32 v1, 4, v0
	v_bitop3_b32 v1, v1, v0, 32 bitop3:0x6c
	v_ashrrev_i32_e32 v0, 31, v0
	v_lshrrev_b32_e32 v0, 26, v0
	v_add_u32_e32 v0, v1, v0
	v_ashrrev_i32_e32 v12, 6, v0
	v_ashrrev_i32_e32 v0, 31, v11
	v_lshrrev_b32_e32 v0, 26, v0
	v_add_u32_e32 v0, v11, v0
	v_ashrrev_i32_e32 v13, 6, v0
	v_lshlrev_b32_e32 v0, 3, v13
	s_lshr_b32 s0, s0, 28
	v_and_b32_e32 v0, -16, v0
	s_add_i32 s0, s2, s0
	v_add_u32_e32 v0, v12, v0
	s_ashr_i32 s12, s0, 4
	s_and_b32 s0, s0, -16
	v_lshrrev_b32_e32 v3, 2, v0
	v_lshlrev_b32_e32 v5, 1, v0
	s_add_i32 s4, s12, 64
	v_lshlrev_b32_e32 v251, 4, v175
	s_lshl_b32 s98, s4, 12
	s_add_u32 s98, s98, 0x120000
	v_add_u32_e32 v250, s98, v251
	v_add_u32_e32 v251, 0x21000, v251
	global_load_dwordx4 v[246:249], v250, s[68:69]
	s_sub_i32 s0, s2, s0
	v_and_b32_e32 v3, 4, v3
	v_and_b32_e32 v4, 3, v12
	v_and_b32_e32 v5, 0x1fffd8, v5
	s_ashr_i32 s5, s4, 31
	s_ashr_i32 s1, s0, 31
	v_or3_b32 v3, v4, v3, v5
	v_mul_i32_i24_e32 v5, 64, v12
	s_lshl_b64 s[8:9], s[4:5], 19
	s_lshl_b64 s[6:7], s[0:1], 19
	v_sub_u32_e32 v1, v1, v5
	s_add_u32 s5, s68, s6
	v_lshlrev_b32_e32 v4, 5, v13
	v_ashrrev_i16_sdwa v1, v2, sext(v1) dst_sel:DWORD dst_unused:UNUSED_PAD src0_sel:DWORD src1_sel:BYTE_0
	s_addc_u32 s11, s69, s7
	v_and_b32_e32 v4, 32, v4
	v_bfe_i32 v14, v1, 0, 16
	s_add_u32 s6, s5, 0xa00000
	v_add_lshl_u32 v1, v4, v14, 1
	s_addc_u32 s7, s11, 0
	s_add_i32 s1, s67, 0
	v_lshl_add_u32 v134, v3, 11, v1
	s_add_i32 m0, s1, 0x10000
	v_lshl_add_u32 v136, v0, 11, v1
	global_load_lds_dwordx4 v134, s[6:7]
	s_add_i32 m0, s1, 0x12000
	s_add_u32 s10, s5, 0xa10000
	global_load_lds_dwordx4 v130, s[6:7]
	s_addc_u32 s11, s11, 0
	s_add_i32 m0, s1, 0x14000
	v_mov_b32_e32 v135, 0
	global_load_lds_dwordx4 v134, s[10:11]
	s_add_i32 m0, s1, 0x16000
	v_mov_b32_e32 v131, v135
	global_load_lds_dwordx4 v130, s[10:11]
	s_add_u32 s10, s68, s8
	s_addc_u32 s11, s69, s9
	s_add_u32 s8, s10, 0xdc00000
	s_addc_u32 s9, s11, 0
	s_add_i32 s5, s1, 0x2000
	s_mov_b32 m0, s1
	s_add_u32 s10, s10, 0xdc40000
	global_load_lds_dwordx4 v136, s[8:9]
	s_mov_b32 m0, s5
	s_addc_u32 s11, s11, 0
	s_add_i32 s18, s1, 0x4000
	global_load_lds_dwordx4 v132, s[8:9]
	s_mov_b32 m0, s18
	s_add_i32 s19, s1, 0x6000
	global_load_lds_dwordx4 v136, s[10:11]
	s_mov_b32 m0, s19
	v_mov_b32_e32 v137, v135
	global_load_lds_dwordx4 v132, s[10:11]
	v_mov_b32_e32 v133, v135
	v_readlane_b32 s10, v255, 17
	v_lshl_add_u64 v[6:7], s[6:7], 0, v[134:135]
	v_lshl_add_u64 v[4:5], s[6:7], 0, v[130:131]
	v_lshl_add_u64 v[0:1], s[8:9], 0, v[136:137]
	s_cmp_lg_u32 s10, 1
	v_lshl_add_u64 v[2:3], s[8:9], 0, v[132:133]
	s_cbranch_scc1 .LBB0_757
	s_barrier
;     __host__ __device__ bool next(int i, Unit& u) const { return at((long)i * G + c, u); }
;     __host__ __device__ bool next(int i, Unit& u) const { if (i != 0 || c >= cnt) return false; u.pm = pm0 + c / nN; u.pn = c % nN; u.k0 = 0; u.nt = ntk; return true; }
; #define PG8_STAGE(bufoff, gbase, voff) do { _Pragma("unroll") for (int _i = 0; _i < 2; ++_i) \
;         __builtin_amdgcn_global_load_lds((const unsigned*)((const char*)(gbase) + (voff)[_i]), (PG8_LAS unsigned*)(lds + (bufoff) + ldsw + _i * 8192), 16, 0, 0); } while (0)
; #define PG8_STAGEA(bufoff, gbase, voff) do { _Pragma("unroll") for (int _i = 0; _i < 2; ++_i) \
;         __builtin_amdgcn_global_load_lds((const unsigned*)((const char*)(gbase) + (voff)[_i]), (PG8_LAS unsigned*)(lds + (bufoff) + ldsw + _i * 8192), 16, 0, AUXA); } while (0)
; #define PG8_WAIT_V(n) asm volatile("s_waitcnt vmcnt(" #n ")" ::: "memory")
; #define PG8_BAR __builtin_amdgcn_s_barrier()
;     ...
;     Unit cur, nxt; int ui = 0;
;     if (!S.next(0, cur)) return;
;     f32x4 acc[2][2][4][2];
; #pragma unroll
;     for (int a = 0; a < 2; ++a)
; #pragma unroll
;         for (int b = 0; b < 2; ++b)
; #pragma unroll
;             for (int m = 0; m < 4; ++m)
; #pragma unroll
;                 for (int n = 0; n < 2; ++n) acc[a][b][m][n] = (f32x4){0.f, 0.f, 0.f, 0.f};
;     ...
;         PG8_STAGE(PG8_SB(1, 0), cB + kstep, voffB); PG8_STAGEA(PG8_SA(1, 0), cA + kstep, voffA); PG8_STAGE(PG8_SB(1, 1), cB + hstepB + kstep, voffB);
;         PG8_WAIT_V(6); PG8_BAR;
.LBB0_757:
	v_and_b32_e32 v15, 15, v11
	v_lshrrev_b32_e32 v16, 1, v11
	v_or_b32_e32 v129, s72, v15
	v_lshlrev_b32_e32 v200, 4, v129
	v_add_u32_e32 v200, 0x21000, v200
	v_and_b32_e32 v16, 24, v16
	v_lshlrev_b32_e32 v17, 6, v129
	v_lshlrev_b32_e32 v128, 1, v16
	s_movk_i32 s10, 0x3c0
	v_and_or_b32 v16, v17, s10, v128
	v_lshlrev_b32_e32 v17, 2, v129
	v_and_b32_e32 v17, 32, v17
	v_readlane_b32 s10, v255, 18
	v_lshlrev_b32_e32 v11, 2, v11
	v_lshl_or_b32 v15, v15, 6, v128
	v_bitop3_b32 v16, v16, s10, v17 bitop3:0xde
	v_and_b32_e32 v11, 32, v11
	v_readlane_b32 s10, v255, 19
	s_add_i32 m0, s1, 0x18000
	s_waitcnt vmcnt(2)
	s_barrier
	v_bitop3_b32 v11, v15, s10, v11 bitop3:0xde
	s_mov_b64 s[10:11], 0x80
	v_lshl_add_u64 v[6:7], v[6:7], 0, s[10:11]
	global_load_lds_dwordx4 v[6:7], off
	v_lshl_add_u64 v[4:5], v[4:5], 0, s[10:11]
	s_add_i32 m0, s1, 0x1a000
	s_add_i32 s20, s1, 0x8000
	s_add_i32 s21, s1, 0xa000
	global_load_lds_dwordx4 v[4:5], off
	v_lshl_add_u64 v[0:1], v[0:1], 0, s[10:11]
	s_mov_b32 m0, s20
	s_add_u32 s14, s6, 0x10080
	global_load_lds_dwordx4 v[0:1], off
	v_lshl_add_u64 v[0:1], v[2:3], 0, s[10:11]
	s_mov_b32 m0, s21
	s_addc_u32 s15, s7, 0
	global_load_lds_dwordx4 v[0:1], off
	s_add_i32 m0, s1, 0x1c000
	v_lshl_add_u64 v[0:1], s[14:15], 0, v[134:135]
	global_load_lds_dwordx4 v[0:1], off
	v_lshl_add_u64 v[0:1], s[14:15], 0, v[130:131]
	s_add_i32 m0, s1, 0x1e000
	s_ashr_i32 s13, s12, 31
	global_load_lds_dwordx4 v[0:1], off
	v_lshlrev_b32_e32 v0, 14, v13
	v_and_b32_e32 v0, 0xffff8000, v0
	s_lshl_b64 s[12:13], s[12:13], 19
	v_lshl_add_u32 v0, v12, 11, v0
	v_and_b32_e32 v1, 1, v13
	v_lshl_or_b32 v0, v1, 6, v0
	s_add_u32 s12, s68, s12
	v_lshl_add_u32 v0, v14, 1, v0
	v_mov_b32_e32 v1, v135
	s_addc_u32 s13, s69, s13
	v_lshl_add_u64 v[138:139], s[12:13], 0, v[0:1]
	v_lshlrev_b32_e32 v0, 14, v8
	v_and_b32_e32 v0, 0xffff8000, v0
	v_lshl_add_u32 v0, v9, 11, v0
	v_and_b32_e32 v1, 1, v8
	s_waitcnt vmcnt(6)
	ds_write_b128 v251, v[246:249]
	v_lshl_or_b32 v0, v1, 6, v0
	s_add_i32 s25, 0, 0x10000
	s_add_i32 s27, 0, 0x14000
	s_add_i32 s29, 0, 0x18000
	s_add_i32 s31, 0, 0x1c000
	v_lshl_add_u32 v0, v10, 1, v0
	v_mov_b32_e32 v1, v135
	v_add_u32_e32 v142, s25, v11
	v_add_u32_e32 v143, s27, v11
	s_add_i32 s25, s25, s67
	s_add_i32 s27, s27, s67
	v_add_u32_e32 v145, s29, v11
	v_add_u32_e32 v146, s31, v11
	s_add_i32 s29, s29, s67
	s_add_i32 s31, s31, s67
	v_lshl_add_u64 v[140:141], s[12:13], 0, v[0:1]
	s_mov_b32 s22, -2
	s_mov_b64 s[12:13], 0xfc40080
	v_add_u32_e32 v144, 0, v16
	s_add_i32 s23, s1, 0xc000
	s_add_i32 s24, s1, 0xe000
	s_add_i32 s26, s25, 0x2000
	s_add_i32 s28, s27, 0x2000
	s_add_i32 s30, s29, 0x2000
	s_add_i32 s34, s31, 0x2000
	v_mov_b32_e32 v0, v135
	v_mov_b32_e32 v2, v135
	v_mov_b32_e32 v3, v135
	v_mov_b32_e32 v4, v135
	v_mov_b32_e32 v5, v135
	v_mov_b32_e32 v6, v135
	v_mov_b32_e32 v7, v135
	v_mov_b32_e32 v16, v135
	v_mov_b32_e32 v17, v135
	v_mov_b32_e32 v18, v135
	v_mov_b32_e32 v19, v135
	v_mov_b32_e32 v20, v135
	v_mov_b32_e32 v21, v135
	v_mov_b32_e32 v22, v135
	v_mov_b32_e32 v23, v135
	v_mov_b32_e32 v32, v135
	v_mov_b32_e32 v33, v135
	v_mov_b32_e32 v34, v135
	v_mov_b32_e32 v35, v135
	v_mov_b32_e32 v36, v135
	v_mov_b32_e32 v37, v135
	v_mov_b32_e32 v38, v135
	v_mov_b32_e32 v39, v135
	v_mov_b32_e32 v48, v135
	v_mov_b32_e32 v49, v135
	v_mov_b32_e32 v50, v135
	v_mov_b32_e32 v51, v135
	v_mov_b32_e32 v52, v135
	v_mov_b32_e32 v53, v135
	v_mov_b32_e32 v54, v135
	v_mov_b32_e32 v55, v135
	v_mov_b32_e32 v8, v135
	v_mov_b32_e32 v9, v135
	v_mov_b32_e32 v10, v135
	v_mov_b32_e32 v11, v135
	v_mov_b32_e32 v12, v135
	v_mov_b32_e32 v13, v135
	v_mov_b32_e32 v14, v135
	v_mov_b32_e32 v15, v135
	v_mov_b32_e32 v24, v135
	v_mov_b32_e32 v25, v135
	v_mov_b32_e32 v26, v135
	v_mov_b32_e32 v27, v135
	v_mov_b32_e32 v28, v135
	v_mov_b32_e32 v29, v135
	v_mov_b32_e32 v30, v135
	v_mov_b32_e32 v31, v135
	v_mov_b32_e32 v40, v135
	v_mov_b32_e32 v41, v135
	v_mov_b32_e32 v42, v135
	v_mov_b32_e32 v43, v135
	v_mov_b32_e32 v44, v135
	v_mov_b32_e32 v45, v135
	v_mov_b32_e32 v46, v135
	v_mov_b32_e32 v47, v135
	v_mov_b32_e32 v56, v135
	v_mov_b32_e32 v57, v135
	v_mov_b32_e32 v58, v135
	v_mov_b32_e32 v59, v135
	v_mov_b32_e32 v60, v135
	v_mov_b32_e32 v61, v135
	v_mov_b32_e32 v62, v135
	v_mov_b32_e32 v63, v135
	v_mov_b32_e32 v64, v135
	v_mov_b32_e32 v65, v135
	v_mov_b32_e32 v66, v135
	v_mov_b32_e32 v67, v135
	v_mov_b32_e32 v68, v135
	v_mov_b32_e32 v69, v135
	v_mov_b32_e32 v70, v135
	v_mov_b32_e32 v71, v135
	v_mov_b32_e32 v80, v135
	v_mov_b32_e32 v81, v135
	v_mov_b32_e32 v82, v135
	v_mov_b32_e32 v83, v135
	v_mov_b32_e32 v84, v135
	v_mov_b32_e32 v85, v135
	v_mov_b32_e32 v86, v135
	v_mov_b32_e32 v87, v135
	v_mov_b32_e32 v96, v135
	v_mov_b32_e32 v97, v135
	v_mov_b32_e32 v98, v135
	v_mov_b32_e32 v99, v135
	v_mov_b32_e32 v100, v135
	v_mov_b32_e32 v101, v135
	v_mov_b32_e32 v102, v135
	v_mov_b32_e32 v103, v135
	v_mov_b32_e32 v112, v135
	v_mov_b32_e32 v113, v135
	v_mov_b32_e32 v114, v135
	v_mov_b32_e32 v115, v135
	v_mov_b32_e32 v116, v135
	v_mov_b32_e32 v117, v135
	v_mov_b32_e32 v118, v135
	v_mov_b32_e32 v119, v135
	v_mov_b32_e32 v72, v135
	v_mov_b32_e32 v73, v135
	v_mov_b32_e32 v74, v135
	v_mov_b32_e32 v75, v135
	v_mov_b32_e32 v76, v135
	v_mov_b32_e32 v77, v135
	v_mov_b32_e32 v78, v135
	v_mov_b32_e32 v79, v135
	v_mov_b32_e32 v88, v135
	v_mov_b32_e32 v89, v135
	v_mov_b32_e32 v90, v135
	v_mov_b32_e32 v91, v135
	v_mov_b32_e32 v92, v135
	v_mov_b32_e32 v93, v135
	v_mov_b32_e32 v94, v135
	v_mov_b32_e32 v95, v135
	v_mov_b32_e32 v104, v135
	v_mov_b32_e32 v105, v135
	v_mov_b32_e32 v106, v135
	v_mov_b32_e32 v107, v135
	v_mov_b32_e32 v108, v135
	v_mov_b32_e32 v109, v135
	v_mov_b32_e32 v110, v135
	v_mov_b32_e32 v111, v135
	v_mov_b32_e32 v120, v135
	v_mov_b32_e32 v121, v135
	v_mov_b32_e32 v122, v135
	v_mov_b32_e32 v123, v135
	v_mov_b32_e32 v124, v135
	v_mov_b32_e32 v125, v135
	v_mov_b32_e32 v126, v135
	v_mov_b32_e32 v127, v135
	s_barrier
	v_readlane_b32 s98, v255, 17
	s_cmp_lg_u32 s98, 1
	s_cbranch_scc1 .Lsprio_2
	s_setprio 1

;     __device__ __forceinline__ void operator()(const f32x4 (&acc)[2][2][4][2], const Unit& u, int wr, int wc, int fr, int fq) const {
;         float rsv[8];
; #pragma unroll
;         for (int idx = 0; idx < 8; ++idx) { const f32x4 q = *(const f32x4*)(rowss + (size_t)(u.pm * BM + (idx >> 2) * HALF + wr * 64 + (idx & 3) * 16 + fr) * 4); rsv[idx] = (q[0] + q[1]) + (q[2] + q[3]); }
; #pragma unroll
;         for (int ai = 0; ai < 2; ++ai)
; #pragma unroll
;             for (int m = 0; m < 4; ++m) {
;                 const int r = u.pm * BM + ai * HALF + wr * 64 + m * 16 + fr;
;                 const float rs = rsqrtf(rsv[ai * 4 + m] * (1.0f / DM) + EPS);
; #pragma unroll
;                 for (int bj = 0; bj < 2; ++bj) {
;                     f32x4 a = acc[ai][bj][m][0] * rs, b = acc[ai][bj][m][1] * rs;
; #pragma unroll
;                     for (int t = 0; t < 4; ++t) { a[t] = fmaxf(a[t], 0.f); a[t] *= a[t]; b[t] = fmaxf(b[t], 0.f); b[t] *= b[t]; }
;                     st8bf(U + (size_t)r * FF + u.pn * BM + wc * 64 + bj * 32 + 8 * fq, a, b);
;                 }
.LBB0_761:
	s_add_u32 s6, s68, 0x120000
	v_lshl_add_u32 v130, s4, 8, v129
	s_addc_u32 s7, s69, 0
	v_ashrrev_i32_e32 v131, 31, v130
	v_or_b32_e32 v148, 16, v130
	v_lshl_add_u64 v[132:133], v[130:131], 4, s[6:7]
	v_ashrrev_i32_e32 v149, 31, v148
	v_or_b32_e32 v146, 32, v130
	v_lshl_add_u64 v[138:139], v[148:149], 4, s[6:7]
	ds_read_b128 v[134:137], v200
	ds_read_b128 v[142:145], v200 offset:256
	v_ashrrev_i32_e32 v147, 31, v146
	v_or_b32_e32 v140, 48, v130
	v_lshl_add_u64 v[132:133], v[146:147], 4, s[6:7]
	v_ashrrev_i32_e32 v141, 31, v140
	v_lshl_add_u64 v[138:139], v[140:141], 4, s[6:7]
	ds_read_b128 v[150:153], v200 offset:512
	ds_read_b128 v[154:157], v200 offset:768
	v_add_u32_e32 v138, 0x80, v130
	v_add_u32_e32 v158, 0x90, v130
	v_ashrrev_i32_e32 v139, 31, v138
	v_ashrrev_i32_e32 v159, 31, v158
	v_lshl_add_u64 v[132:133], v[138:139], 4, s[6:7]
	v_lshl_add_u64 v[162:163], v[158:159], 4, s[6:7]
	ds_read_b128 v[158:161], v200 offset:2048
	s_nop 0
	ds_read_b128 v[162:165], v200 offset:2304
	v_add_u32_e32 v132, 0xa0, v130
	v_ashrrev_i32_e32 v133, 31, v132
	v_lshl_add_u64 v[132:133], v[132:133], 4, s[6:7]
	ds_read_b128 v[166:169], v200 offset:2560
	v_add_u32_e32 v132, 0xb0, v130
	v_ashrrev_i32_e32 v133, 31, v132
	v_lshl_add_u64 v[132:133], v[132:133], 4, s[6:7]
	s_mov_b32 s8, 0x358637bd
	ds_read_b128 v[170:173], v200 offset:2816
	s_mov_b32 s4, 0x3a800000
	s_mov_b32 s5, 0x800000
	v_mov_b64_e32 v[132:133], s[8:9]
	s_add_u32 s10, s68, 0x3200000
	s_addc_u32 s11, s69, 0
	s_lshl_b32 s8, s0, 8
	v_lshlrev_b64 v[130:131], 13, v[130:131]
	s_ashr_i32 s9, s8, 31
	v_lshl_add_u64 v[130:131], s[10:11], 0, v[130:131]
	s_lshl_b64 s[8:9], s[8:9], 1
	s_mov_b32 s1, 0
	s_lshl_b32 s0, s48, 7
	v_lshl_add_u64 v[130:131], v[130:131], 0, s[8:9]
	v_mov_b32_e32 v129, 0
	v_lshl_add_u64 v[130:131], v[130:131], 0, s[0:1]
	v_lshl_add_u64 v[130:131], v[130:131], 0, v[128:129]
	s_mov_b64 s[6:7], 0x120000
	s_waitcnt vmcnt(0)
	s_waitcnt lgkmcnt(0)
	v_mov_b32_e32 v176, v135
	v_mov_b32_e32 v177, v136
	v_mov_b32_e32 v135, v137
	v_mov_b32_e32 v136, v143
	v_mov_b32_e32 v137, v144
	v_mov_b32_e32 v143, v145
	v_pk_add_f32 v[134:135], v[176:177], v[134:135]
	v_mov_b32_e32 v144, v151
	v_mov_b32_e32 v145, v152
	v_mov_b32_e32 v151, v153
	v_pk_add_f32 v[136:137], v[136:137], v[142:143]
	v_pk_add_f32 v[150:151], v[144:145], v[150:151]
	v_mov_b32_e32 v145, v134
	v_mov_b32_e32 v144, v136
	v_mov_b32_e32 v134, v137
	v_mov_b32_e32 v152, v155
	v_mov_b32_e32 v153, v156
	v_mov_b32_e32 v155, v157
	v_pk_add_f32 v[134:135], v[144:145], v[134:135]
	v_pk_add_f32 v[152:153], v[152:153], v[154:155]
	v_pk_fma_f32 v[154:155], v[134:135], s[4:5], v[132:133] op_sel_hi:[1,0,0]
	v_mov_b32_e32 v156, v159
	v_mul_f32_e32 v134, 0x4b800000, v155
	v_cmp_gt_f32_e32 vcc, s5, v155
	v_mov_b32_e32 v157, v160
	v_mov_b32_e32 v159, v161
	v_cndmask_b32_e32 v134, v155, v134, vcc
	v_rsq_f32_e32 v155, v134
	v_pk_add_f32 v[142:143], v[156:157], v[158:159]
	v_mov_b32_e32 v160, v163
	v_mov_b32_e32 v161, v164
	v_mul_f32_e32 v156, 0x45800000, v155
	v_cndmask_b32_e32 v156, v155, v156, vcc
	v_pk_mul_f32 v[120:121], v[120:121], v[156:157] op_sel_hi:[1,0]
	v_pk_mul_f32 v[126:127], v[126:127], v[156:157] op_sel_hi:[1,0]
	v_pk_mul_f32 v[124:125], v[124:125], v[156:157] op_sel_hi:[1,0]
	v_pk_mul_f32 v[122:123], v[122:123], v[156:157] op_sel_hi:[1,0]
	v_max_f32_e32 v120, 0, v120
	v_max_f32_e32 v121, 0, v121
	v_mov_b32_e32 v163, v165
	v_max_f32_e32 v124, 0, v124
	v_max_f32_e32 v125, 0, v125
	v_pk_mul_f32 v[158:159], v[120:121], v[120:121]
	v_max_f32_e32 v120, 0, v126
	v_max_f32_e32 v122, 0, v122
	v_max_f32_e32 v121, 0, v127
	v_max_f32_e32 v123, 0, v123
	v_pk_add_f32 v[144:145], v[160:161], v[162:163]
	v_pk_mul_f32 v[124:125], v[124:125], v[124:125]
	v_pk_mul_f32 v[126:127], v[120:121], v[120:121]
	v_pk_mul_f32 v[160:161], v[122:123], v[122:123]
	v_pk_mul_f32 v[114:115], v[114:115], v[156:157] op_sel_hi:[1,0]
	v_cvt_pk_bf16_f32 v120, v124, v125
	v_cvt_pk_bf16_f32 v121, v126, v127
	v_cvt_pk_bf16_f32 v122, v158, v159
	v_cvt_pk_bf16_f32 v123, v160, v161
	v_pk_mul_f32 v[116:117], v[116:117], v[156:157] op_sel_hi:[1,0]
	v_pk_mul_f32 v[112:113], v[112:113], v[156:157] op_sel_hi:[1,0]
	v_max_f32_e32 v114, 0, v114
	v_max_f32_e32 v115, 0, v115
	global_store_dwordx4 v[130:131], v[120:123], off
	v_pk_mul_f32 v[118:119], v[118:119], v[156:157] op_sel_hi:[1,0]
	v_max_f32_e32 v116, 0, v116
	v_max_f32_e32 v112, 0, v112
	v_max_f32_e32 v117, 0, v117
	v_max_f32_e32 v113, 0, v113
	v_pk_mul_f32 v[122:123], v[114:115], v[114:115]
	v_mul_f32_e32 v114, 0x4b800000, v154
	v_cmp_gt_f32_e32 vcc, s5, v154
	v_pk_mul_f32 v[116:117], v[116:117], v[116:117]
	v_pk_mul_f32 v[120:121], v[112:113], v[112:113]
	v_max_f32_e32 v112, 0, v118
	v_max_f32_e32 v113, 0, v119
	v_cndmask_b32_e32 v114, v154, v114, vcc
	v_pk_mul_f32 v[118:119], v[112:113], v[112:113]
	v_cvt_pk_bf16_f32 v112, v116, v117
	v_rsq_f32_e32 v116, v114
	v_cvt_pk_bf16_f32 v113, v118, v119
	v_cvt_pk_bf16_f32 v114, v120, v121
	v_cvt_pk_bf16_f32 v115, v122, v123
	global_store_dwordx4 v[130:131], v[112:115], off offset:64
	v_mov_b32_e32 v164, v167
	v_mov_b32_e32 v165, v168
	v_mul_f32_e32 v112, 0x45800000, v116
	v_cndmask_b32_e32 v112, v116, v112, vcc
	v_pk_mul_f32 v[104:105], v[104:105], v[112:113] op_sel_hi:[1,0]
	v_pk_mul_f32 v[110:111], v[110:111], v[112:113] op_sel_hi:[1,0]
	v_max_f32_e32 v104, 0, v104
	v_max_f32_e32 v105, 0, v105
	v_lshlrev_b64 v[114:115], 13, v[148:149]
	v_pk_mul_f32 v[116:117], v[104:105], v[104:105]
	v_max_f32_e32 v104, 0, v110
	v_max_f32_e32 v105, 0, v111
	v_pk_mul_f32 v[108:109], v[108:109], v[112:113] op_sel_hi:[1,0]
	v_pk_mul_f32 v[106:107], v[106:107], v[112:113] op_sel_hi:[1,0]
;     __device__ __forceinline__ void operator()(const f32x4 (&acc)[2][2][4][2], const Unit& u, int wr, int wc, int fr, int fq) const {
;     ...
; #pragma unroll
;         for (int ai = 0; ai < 2; ++ai)
; #pragma unroll
;             for (int m = 0; m < 4; ++m) {
;                 const int r = u.pm * BM + ai * HALF + wr * 64 + m * 16 + fr;
;                 const float rs = rsqrtf(rsv[ai * 4 + m] * (1.0f / DM) + EPS);
; #pragma unroll
;                 for (int bj = 0; bj < 2; ++bj) {
;                     f32x4 a = acc[ai][bj][m][0] * rs, b = acc[ai][bj][m][1] * rs;
; #pragma unroll
;                     for (int t = 0; t < 4; ++t) { a[t] = fmaxf(a[t], 0.f); a[t] *= a[t]; b[t] = fmaxf(b[t], 0.f); b[t] *= b[t]; }
;                     st8bf(U + (size_t)r * FF + u.pn * BM + wc * 64 + bj * 32 + 8 * fq, a, b);
;                 }
	v_pk_mul_f32 v[110:111], v[104:105], v[104:105]
	v_lshl_add_u64 v[104:105], s[10:11], 0, v[114:115]
	v_max_f32_e32 v108, 0, v108
	v_max_f32_e32 v109, 0, v109
	v_max_f32_e32 v106, 0, v106
	v_max_f32_e32 v107, 0, v107
	v_lshl_add_u64 v[104:105], v[104:105], 0, s[8:9]
	v_pk_mul_f32 v[108:109], v[108:109], v[108:109]
	v_pk_mul_f32 v[118:119], v[106:107], v[106:107]
	v_lshl_add_u64 v[104:105], v[104:105], 0, s[0:1]
	v_pk_mul_f32 v[96:97], v[96:97], v[112:113] op_sel_hi:[1,0]
	v_lshl_add_u64 v[114:115], v[104:105], 0, v[128:129]
	v_cvt_pk_bf16_f32 v104, v108, v109
	v_cvt_pk_bf16_f32 v105, v110, v111
	v_cvt_pk_bf16_f32 v106, v116, v117
	v_cvt_pk_bf16_f32 v107, v118, v119
	v_pk_mul_f32 v[102:103], v[102:103], v[112:113] op_sel_hi:[1,0]
	v_pk_mul_f32 v[100:101], v[100:101], v[112:113] op_sel_hi:[1,0]
	v_pk_mul_f32 v[98:99], v[98:99], v[112:113] op_sel_hi:[1,0]
	v_max_f32_e32 v96, 0, v96
	v_max_f32_e32 v97, 0, v97
	global_store_dwordx4 v[114:115], v[104:107], off
	v_max_f32_e32 v100, 0, v100
	v_max_f32_e32 v101, 0, v101
	v_pk_mul_f32 v[104:105], v[96:97], v[96:97]
	v_max_f32_e32 v96, 0, v102
	v_max_f32_e32 v98, 0, v98
	v_max_f32_e32 v97, 0, v103
	v_max_f32_e32 v99, 0, v99
	v_pk_mul_f32 v[100:101], v[100:101], v[100:101]
	v_pk_mul_f32 v[102:103], v[96:97], v[96:97]
	v_pk_mul_f32 v[106:107], v[98:99], v[98:99]
	v_cvt_pk_bf16_f32 v96, v100, v101
	v_cvt_pk_bf16_f32 v97, v102, v103
	v_cvt_pk_bf16_f32 v98, v104, v105
	v_cvt_pk_bf16_f32 v99, v106, v107
	global_store_dwordx4 v[114:115], v[96:99], off offset:64
	v_mov_b32_e32 v167, v169
	v_mov_b32_e32 v168, v171
	v_mov_b32_e32 v98, v152
	v_mov_b32_e32 v99, v150
	v_mov_b32_e32 v150, v153
	v_pk_add_f32 v[98:99], v[98:99], v[150:151]
	v_lshlrev_b64 v[96:97], 13, v[146:147]
	v_pk_fma_f32 v[98:99], v[98:99], s[4:5], v[132:133] op_sel_hi:[1,0,0]
	v_lshl_add_u64 v[96:97], s[10:11], 0, v[96:97]
	v_mul_f32_e32 v100, 0x4b800000, v99
	v_cmp_gt_f32_e32 vcc, s5, v99
	v_lshl_add_u64 v[96:97], v[96:97], 0, s[8:9]
	v_lshl_add_u64 v[96:97], v[96:97], 0, s[0:1]
	v_cndmask_b32_e32 v99, v99, v100, vcc
	v_rsq_f32_e32 v99, v99
	v_lshl_add_u64 v[96:97], v[96:97], 0, v[128:129]
	v_mov_b32_e32 v169, v172
	v_mov_b32_e32 v171, v173
	v_mul_f32_e32 v100, 0x45800000, v99
	v_cndmask_b32_e32 v100, v99, v100, vcc
	v_pk_mul_f32 v[88:89], v[88:89], v[100:101] op_sel_hi:[1,0]
	v_pk_mul_f32 v[94:95], v[94:95], v[100:101] op_sel_hi:[1,0]
	v_pk_mul_f32 v[92:93], v[92:93], v[100:101] op_sel_hi:[1,0]
	v_pk_mul_f32 v[90:91], v[90:91], v[100:101] op_sel_hi:[1,0]
	v_max_f32_e32 v88, 0, v88
	v_max_f32_e32 v89, 0, v89
	v_max_f32_e32 v92, 0, v92
	v_max_f32_e32 v93, 0, v93
	v_pk_mul_f32 v[102:103], v[88:89], v[88:89]
	v_max_f32_e32 v88, 0, v94
	v_max_f32_e32 v90, 0, v90
	v_max_f32_e32 v89, 0, v95
	v_max_f32_e32 v91, 0, v91
	v_pk_mul_f32 v[92:93], v[92:93], v[92:93]
	v_pk_mul_f32 v[94:95], v[88:89], v[88:89]
	v_pk_mul_f32 v[104:105], v[90:91], v[90:91]
	v_pk_mul_f32 v[82:83], v[82:83], v[100:101] op_sel_hi:[1,0]
	v_cvt_pk_bf16_f32 v88, v92, v93
	v_cvt_pk_bf16_f32 v89, v94, v95
	v_cvt_pk_bf16_f32 v90, v102, v103
	v_cvt_pk_bf16_f32 v91, v104, v105
	v_pk_mul_f32 v[84:85], v[84:85], v[100:101] op_sel_hi:[1,0]
	v_pk_mul_f32 v[80:81], v[80:81], v[100:101] op_sel_hi:[1,0]
	v_max_f32_e32 v82, 0, v82
	v_max_f32_e32 v83, 0, v83
	global_store_dwordx4 v[96:97], v[88:91], off
	v_pk_mul_f32 v[86:87], v[86:87], v[100:101] op_sel_hi:[1,0]
	v_max_f32_e32 v84, 0, v84
	v_max_f32_e32 v80, 0, v80
	v_max_f32_e32 v85, 0, v85
	v_max_f32_e32 v81, 0, v81
	v_pk_mul_f32 v[90:91], v[82:83], v[82:83]
	v_mul_f32_e32 v82, 0x4b800000, v98
	v_cmp_gt_f32_e32 vcc, s5, v98
	v_pk_mul_f32 v[84:85], v[84:85], v[84:85]
	v_pk_mul_f32 v[88:89], v[80:81], v[80:81]
	v_max_f32_e32 v80, 0, v86
	v_max_f32_e32 v81, 0, v87
	v_cndmask_b32_e32 v82, v98, v82, vcc
	v_pk_mul_f32 v[86:87], v[80:81], v[80:81]
	v_cvt_pk_bf16_f32 v80, v84, v85
	v_rsq_f32_e32 v84, v82
	v_cvt_pk_bf16_f32 v81, v86, v87
	v_cvt_pk_bf16_f32 v82, v88, v89
	v_cvt_pk_bf16_f32 v83, v90, v91
	global_store_dwordx4 v[96:97], v[80:83], off offset:64
	v_pk_add_f32 v[134:135], v[164:165], v[166:167]
	v_pk_add_f32 v[136:137], v[168:169], v[170:171]
	v_mul_f32_e32 v80, 0x45800000, v84
	v_cndmask_b32_e32 v80, v84, v80, vcc
	v_pk_mul_f32 v[72:73], v[72:73], v[80:81] op_sel_hi:[1,0]
	v_pk_mul_f32 v[78:79], v[78:79], v[80:81] op_sel_hi:[1,0]
	v_max_f32_e32 v72, 0, v72
	v_max_f32_e32 v73, 0, v73
	v_lshlrev_b64 v[82:83], 13, v[140:141]
	v_pk_mul_f32 v[84:85], v[72:73], v[72:73]
	v_max_f32_e32 v72, 0, v78
	v_max_f32_e32 v73, 0, v79
	v_pk_mul_f32 v[76:77], v[76:77], v[80:81] op_sel_hi:[1,0]
	v_pk_mul_f32 v[74:75], v[74:75], v[80:81] op_sel_hi:[1,0]
	v_pk_mul_f32 v[78:79], v[72:73], v[72:73]
	v_lshl_add_u64 v[72:73], s[10:11], 0, v[82:83]
	v_max_f32_e32 v76, 0, v76
	v_max_f32_e32 v77, 0, v77
	v_max_f32_e32 v74, 0, v74
	v_max_f32_e32 v75, 0, v75
	v_lshl_add_u64 v[72:73], v[72:73], 0, s[8:9]
	v_pk_mul_f32 v[76:77], v[76:77], v[76:77]
	v_pk_mul_f32 v[86:87], v[74:75], v[74:75]
	v_lshl_add_u64 v[72:73], v[72:73], 0, s[0:1]
	v_pk_mul_f32 v[64:65], v[64:65], v[80:81] op_sel_hi:[1,0]
	v_lshl_add_u64 v[82:83], v[72:73], 0, v[128:129]
	v_cvt_pk_bf16_f32 v72, v76, v77
	v_cvt_pk_bf16_f32 v73, v78, v79
	v_cvt_pk_bf16_f32 v74, v84, v85
	v_cvt_pk_bf16_f32 v75, v86, v87
	v_pk_mul_f32 v[70:71], v[70:71], v[80:81] op_sel_hi:[1,0]
	v_pk_mul_f32 v[68:69], v[68:69], v[80:81] op_sel_hi:[1,0]
	v_pk_mul_f32 v[66:67], v[66:67], v[80:81] op_sel_hi:[1,0]
	v_max_f32_e32 v64, 0, v64
	v_max_f32_e32 v65, 0, v65
	global_store_dwordx4 v[82:83], v[72:75], off
	v_max_f32_e32 v68, 0, v68
	v_max_f32_e32 v69, 0, v69
	v_pk_mul_f32 v[72:73], v[64:65], v[64:65]
	v_max_f32_e32 v64, 0, v70
;     __device__ __forceinline__ void operator()(const f32x4 (&acc)[2][2][4][2], const Unit& u, int wr, int wc, int fr, int fq) const {
;     ...
; #pragma unroll
;         for (int ai = 0; ai < 2; ++ai)
; #pragma unroll
;             for (int m = 0; m < 4; ++m) {
;                 const int r = u.pm * BM + ai * HALF + wr * 64 + m * 16 + fr;
;                 const float rs = rsqrtf(rsv[ai * 4 + m] * (1.0f / DM) + EPS);
; #pragma unroll
;                 for (int bj = 0; bj < 2; ++bj) {
;                     f32x4 a = acc[ai][bj][m][0] * rs, b = acc[ai][bj][m][1] * rs;
; #pragma unroll
;                     for (int t = 0; t < 4; ++t) { a[t] = fmaxf(a[t], 0.f); a[t] *= a[t]; b[t] = fmaxf(b[t], 0.f); b[t] *= b[t]; }
;                     st8bf(U + (size_t)r * FF + u.pn * BM + wc * 64 + bj * 32 + 8 * fq, a, b);
;                 }
	v_max_f32_e32 v66, 0, v66
	v_max_f32_e32 v65, 0, v71
	v_max_f32_e32 v67, 0, v67
	v_pk_mul_f32 v[68:69], v[68:69], v[68:69]
	v_pk_mul_f32 v[70:71], v[64:65], v[64:65]
	v_pk_mul_f32 v[74:75], v[66:67], v[66:67]
	v_cvt_pk_bf16_f32 v64, v68, v69
	v_cvt_pk_bf16_f32 v65, v70, v71
	v_cvt_pk_bf16_f32 v66, v72, v73
	v_cvt_pk_bf16_f32 v67, v74, v75
	global_store_dwordx4 v[82:83], v[64:67], off offset:64
	s_nop 1
	v_mov_b32_e32 v66, v144
	v_mov_b32_e32 v67, v142
	v_mov_b32_e32 v142, v145
	v_pk_add_f32 v[66:67], v[66:67], v[142:143]
	v_lshlrev_b64 v[64:65], 13, v[138:139]
	v_pk_fma_f32 v[66:67], v[66:67], s[4:5], v[132:133] op_sel_hi:[1,0,0]
	v_lshl_add_u64 v[64:65], s[10:11], 0, v[64:65]
	v_mul_f32_e32 v68, 0x4b800000, v67
	v_cmp_gt_f32_e32 vcc, s5, v67
	v_lshl_add_u64 v[64:65], v[64:65], 0, s[8:9]
	v_lshl_add_u64 v[64:65], v[64:65], 0, s[0:1]
	v_cndmask_b32_e32 v67, v67, v68, vcc
	v_rsq_f32_e32 v67, v67
	v_lshl_add_u64 v[64:65], v[64:65], 0, v[128:129]
	s_mov_b32 s0, 0x120000
	v_mul_f32_e32 v68, 0x45800000, v67
	v_cndmask_b32_e32 v68, v67, v68, vcc
	v_pk_mul_f32 v[56:57], v[56:57], v[68:69] op_sel_hi:[1,0]
	v_pk_mul_f32 v[62:63], v[62:63], v[68:69] op_sel_hi:[1,0]
	v_pk_mul_f32 v[60:61], v[60:61], v[68:69] op_sel_hi:[1,0]
	v_pk_mul_f32 v[58:59], v[58:59], v[68:69] op_sel_hi:[1,0]
	v_max_f32_e32 v56, 0, v56
	v_max_f32_e32 v57, 0, v57
	v_max_f32_e32 v60, 0, v60
	v_max_f32_e32 v61, 0, v61
	v_pk_mul_f32 v[70:71], v[56:57], v[56:57]
	v_max_f32_e32 v56, 0, v62
	v_max_f32_e32 v58, 0, v58
	v_max_f32_e32 v57, 0, v63
	v_max_f32_e32 v59, 0, v59
	v_pk_mul_f32 v[60:61], v[60:61], v[60:61]
	v_pk_mul_f32 v[62:63], v[56:57], v[56:57]
	v_pk_mul_f32 v[72:73], v[58:59], v[58:59]
	v_pk_mul_f32 v[50:51], v[50:51], v[68:69] op_sel_hi:[1,0]
	v_cvt_pk_bf16_f32 v56, v60, v61
	v_cvt_pk_bf16_f32 v57, v62, v63
	v_cvt_pk_bf16_f32 v58, v70, v71
	v_cvt_pk_bf16_f32 v59, v72, v73
	v_pk_mul_f32 v[52:53], v[52:53], v[68:69] op_sel_hi:[1,0]
	v_pk_mul_f32 v[48:49], v[48:49], v[68:69] op_sel_hi:[1,0]
	v_max_f32_e32 v50, 0, v50
	v_max_f32_e32 v51, 0, v51
	global_store_dwordx4 v[64:65], v[56:59], off
	v_pk_mul_f32 v[54:55], v[54:55], v[68:69] op_sel_hi:[1,0]
	v_max_f32_e32 v52, 0, v52
	v_max_f32_e32 v48, 0, v48
	v_max_f32_e32 v53, 0, v53
	v_max_f32_e32 v49, 0, v49
	v_pk_mul_f32 v[58:59], v[50:51], v[50:51]
	v_mul_f32_e32 v50, 0x4b800000, v66
	v_cmp_gt_f32_e32 vcc, s5, v66
	v_pk_mul_f32 v[52:53], v[52:53], v[52:53]
	v_pk_mul_f32 v[56:57], v[48:49], v[48:49]
	v_max_f32_e32 v48, 0, v54
	v_max_f32_e32 v49, 0, v55
	v_cndmask_b32_e32 v50, v66, v50, vcc
	v_pk_mul_f32 v[54:55], v[48:49], v[48:49]
	v_cvt_pk_bf16_f32 v48, v52, v53
	v_rsq_f32_e32 v52, v50
	v_cvt_pk_bf16_f32 v49, v54, v55
	v_cvt_pk_bf16_f32 v50, v56, v57
	v_cvt_pk_bf16_f32 v51, v58, v59
	global_store_dwordx4 v[64:65], v[48:51], off offset:64
	v_lshl_add_u64 v[54:55], v[130:131], 0, s[6:7]
	s_mov_b64 s[6:7], 0x140000
	v_mul_f32_e32 v48, 0x45800000, v52
	v_cndmask_b32_e32 v48, v52, v48, vcc
	v_pk_mul_f32 v[44:45], v[44:45], v[48:49] op_sel_hi:[1,0]
	v_pk_mul_f32 v[40:41], v[40:41], v[48:49] op_sel_hi:[1,0]
	v_pk_mul_f32 v[46:47], v[46:47], v[48:49] op_sel_hi:[1,0]
	v_pk_mul_f32 v[42:43], v[42:43], v[48:49] op_sel_hi:[1,0]
	v_max_f32_e32 v44, 0, v44
	v_max_f32_e32 v40, 0, v40
	v_max_f32_e32 v45, 0, v45
	v_max_f32_e32 v41, 0, v41
	v_pk_mul_f32 v[44:45], v[44:45], v[44:45]
	v_pk_mul_f32 v[50:51], v[40:41], v[40:41]
	v_max_f32_e32 v40, 0, v46
	v_max_f32_e32 v42, 0, v42
	v_max_f32_e32 v41, 0, v47
	v_max_f32_e32 v43, 0, v43
	v_pk_mul_f32 v[46:47], v[40:41], v[40:41]
	v_pk_mul_f32 v[52:53], v[42:43], v[42:43]
	v_cvt_pk_bf16_f32 v40, v44, v45
	v_add_co_u32_e32 v44, vcc, s0, v130
	v_pk_mul_f32 v[32:33], v[32:33], v[48:49] op_sel_hi:[1,0]
	v_cvt_pk_bf16_f32 v41, v46, v47
	v_cvt_pk_bf16_f32 v42, v50, v51
	v_cvt_pk_bf16_f32 v43, v52, v53
	v_addc_co_u32_e32 v45, vcc, 0, v131, vcc
	v_pk_mul_f32 v[38:39], v[38:39], v[48:49] op_sel_hi:[1,0]
	v_pk_mul_f32 v[36:37], v[36:37], v[48:49] op_sel_hi:[1,0]
	v_pk_mul_f32 v[34:35], v[34:35], v[48:49] op_sel_hi:[1,0]
	v_max_f32_e32 v32, 0, v32
	v_max_f32_e32 v33, 0, v33
	global_store_dwordx4 v[44:45], v[40:43], off
	v_max_f32_e32 v36, 0, v36
	v_max_f32_e32 v37, 0, v37
	v_pk_mul_f32 v[40:41], v[32:33], v[32:33]
	v_max_f32_e32 v32, 0, v38
	v_max_f32_e32 v34, 0, v34
	v_max_f32_e32 v33, 0, v39
	v_max_f32_e32 v35, 0, v35
	v_pk_mul_f32 v[36:37], v[36:37], v[36:37]
	v_pk_mul_f32 v[38:39], v[32:33], v[32:33]
	v_pk_mul_f32 v[42:43], v[34:35], v[34:35]
	v_cvt_pk_bf16_f32 v32, v36, v37
	v_cvt_pk_bf16_f32 v33, v38, v39
	v_cvt_pk_bf16_f32 v34, v40, v41
	v_cvt_pk_bf16_f32 v35, v42, v43
	global_store_dwordx4 v[54:55], v[32:35], off offset:64
	s_mov_b32 s0, 0x140000
	s_nop 0
	v_mov_b32_e32 v32, v136
	v_mov_b32_e32 v33, v134
	v_mov_b32_e32 v134, v137
	v_pk_add_f32 v[32:33], v[32:33], v[134:135]
	s_nop 0
	v_pk_fma_f32 v[32:33], v[32:33], s[4:5], v[132:133] op_sel_hi:[1,0,0]
	s_nop 0
	v_mul_f32_e32 v34, 0x4b800000, v33
	v_cmp_gt_f32_e32 vcc, s5, v33
	s_nop 1
	v_cndmask_b32_e32 v33, v33, v34, vcc
	v_rsq_f32_e32 v33, v33
	v_lshl_add_u64 v[34:35], v[130:131], 0, s[6:7]
	v_mul_f32_e32 v36, 0x45800000, v33
	v_cndmask_b32_e32 v36, v33, v36, vcc
	v_pk_mul_f32 v[28:29], v[28:29], v[36:37] op_sel_hi:[1,0]
	v_pk_mul_f32 v[24:25], v[24:25], v[36:37] op_sel_hi:[1,0]
	v_pk_mul_f32 v[30:31], v[30:31], v[36:37] op_sel_hi:[1,0]
	v_pk_mul_f32 v[26:27], v[26:27], v[36:37] op_sel_hi:[1,0]
;     __device__ __forceinline__ void operator()(const f32x4 (&acc)[2][2][4][2], const Unit& u, int wr, int wc, int fr, int fq) const {
;     ...
; #pragma unroll
;         for (int ai = 0; ai < 2; ++ai)
; #pragma unroll
;             for (int m = 0; m < 4; ++m) {
;                 const int r = u.pm * BM + ai * HALF + wr * 64 + m * 16 + fr;
;                 const float rs = rsqrtf(rsv[ai * 4 + m] * (1.0f / DM) + EPS);
; #pragma unroll
;                 for (int bj = 0; bj < 2; ++bj) {
;                     f32x4 a = acc[ai][bj][m][0] * rs, b = acc[ai][bj][m][1] * rs;
; #pragma unroll
;                     for (int t = 0; t < 4; ++t) { a[t] = fmaxf(a[t], 0.f); a[t] *= a[t]; b[t] = fmaxf(b[t], 0.f); b[t] *= b[t]; }
;                     st8bf(U + (size_t)r * FF + u.pn * BM + wc * 64 + bj * 32 + 8 * fq, a, b);
;                 }
; DI void retout_load(const Params& P, int ru, int tid, int wave, int lane, OutRegs& R) {
;     const bf16_t* Z = (const bf16_t*)(P.ws + WS_Z);
;     bool samp; int b, c, h, row0; ret_decode(ru, samp, b, c, h, row0);
; #pragma unroll
;     for (int i = 0; i < 2; ++i) { const int v = tid + 512 * i, j = v >> 4, d0 = (v & 15) * 8; const bf16_t* zr = Z + (size_t)(row0 + j) * INW;
;         R.q[i] = __builtin_nontemporal_load((const u32x4*)(zr + 768 + 128 * h + d0)); R.k[i] = __builtin_nontemporal_load((const u32x4*)(zr + 1280 + 128 * h + d0)); R.v[i] = __builtin_nontemporal_load((const u32x4*)(zr + 1792 + 128 * h + d0)); }
;     const bf16_t* S = (const bf16_t*)(P.ws + WS_SB) + ((size_t)(b * 32 + (c > 0 ? c - 1 : 0)) * 4 + h) * 16384;
; #pragma unroll
;     for (int i = 0; i < 4; ++i) { const int v = tid + 512 * i, dk = v >> 4, e0 = (v & 15) * 8; R.s[i] = (u32x4){0u, 0u, 0u, 0u}; if (c > 0) R.s[i] = __builtin_nontemporal_load((const u32x4*)(S + dk * 128 + e0)); }
	v_max_f32_e32 v28, 0, v28
	v_max_f32_e32 v24, 0, v24
	v_max_f32_e32 v29, 0, v29
	v_max_f32_e32 v25, 0, v25
	v_pk_mul_f32 v[28:29], v[28:29], v[28:29]
	v_pk_mul_f32 v[38:39], v[24:25], v[24:25]
	v_max_f32_e32 v24, 0, v30
	v_max_f32_e32 v26, 0, v26
	v_max_f32_e32 v25, 0, v31
	v_max_f32_e32 v27, 0, v27
	v_pk_mul_f32 v[30:31], v[24:25], v[24:25]
	v_pk_mul_f32 v[40:41], v[26:27], v[26:27]
	v_cvt_pk_bf16_f32 v24, v28, v29
	v_add_co_u32_e32 v28, vcc, s0, v130
	v_pk_mul_f32 v[18:19], v[18:19], v[36:37] op_sel_hi:[1,0]
	v_cvt_pk_bf16_f32 v25, v30, v31
	v_cvt_pk_bf16_f32 v26, v38, v39
	v_cvt_pk_bf16_f32 v27, v40, v41
	v_addc_co_u32_e32 v29, vcc, 0, v131, vcc
	v_pk_mul_f32 v[20:21], v[20:21], v[36:37] op_sel_hi:[1,0]
	v_pk_mul_f32 v[16:17], v[16:17], v[36:37] op_sel_hi:[1,0]
	v_max_f32_e32 v18, 0, v18
	v_max_f32_e32 v19, 0, v19
	global_store_dwordx4 v[28:29], v[24:27], off
	v_pk_mul_f32 v[22:23], v[22:23], v[36:37] op_sel_hi:[1,0]
	v_max_f32_e32 v20, 0, v20
	v_max_f32_e32 v16, 0, v16
	v_max_f32_e32 v21, 0, v21
	v_max_f32_e32 v17, 0, v17
	v_pk_mul_f32 v[26:27], v[18:19], v[18:19]
	v_mul_f32_e32 v18, 0x4b800000, v32
	v_cmp_gt_f32_e32 vcc, s5, v32
	v_pk_mul_f32 v[20:21], v[20:21], v[20:21]
	v_pk_mul_f32 v[24:25], v[16:17], v[16:17]
	v_max_f32_e32 v16, 0, v22
	v_max_f32_e32 v17, 0, v23
	v_cndmask_b32_e32 v18, v32, v18, vcc
	v_pk_mul_f32 v[22:23], v[16:17], v[16:17]
	v_cvt_pk_bf16_f32 v16, v20, v21
	v_rsq_f32_e32 v20, v18
	v_cvt_pk_bf16_f32 v17, v22, v23
	v_cvt_pk_bf16_f32 v18, v24, v25
	v_cvt_pk_bf16_f32 v19, v26, v27
	global_store_dwordx4 v[34:35], v[16:19], off offset:64
	s_mov_b32 s0, 0x160000
	s_mov_b64 s[4:5], 0x160000
	v_mul_f32_e32 v16, 0x45800000, v20
	v_cndmask_b32_e32 v16, v20, v16, vcc
	v_pk_mul_f32 v[12:13], v[12:13], v[16:17] op_sel_hi:[1,0]
	v_pk_mul_f32 v[8:9], v[8:9], v[16:17] op_sel_hi:[1,0]
	v_pk_mul_f32 v[14:15], v[14:15], v[16:17] op_sel_hi:[1,0]
	v_pk_mul_f32 v[10:11], v[10:11], v[16:17] op_sel_hi:[1,0]
	v_max_f32_e32 v12, 0, v12
	v_max_f32_e32 v8, 0, v8
	v_max_f32_e32 v13, 0, v13
	v_max_f32_e32 v9, 0, v9
	v_pk_mul_f32 v[12:13], v[12:13], v[12:13]
	v_pk_mul_f32 v[18:19], v[8:9], v[8:9]
	v_max_f32_e32 v8, 0, v14
	v_max_f32_e32 v10, 0, v10
	v_max_f32_e32 v9, 0, v15
	v_max_f32_e32 v11, 0, v11
	v_pk_mul_f32 v[14:15], v[8:9], v[8:9]
	v_pk_mul_f32 v[20:21], v[10:11], v[10:11]
	v_cvt_pk_bf16_f32 v8, v12, v13
	v_add_co_u32_e32 v12, vcc, s0, v130
	v_pk_mul_f32 v[0:1], v[0:1], v[16:17] op_sel_hi:[1,0]
	v_cvt_pk_bf16_f32 v9, v14, v15
	v_cvt_pk_bf16_f32 v10, v18, v19
	v_cvt_pk_bf16_f32 v11, v20, v21
	v_addc_co_u32_e32 v13, vcc, 0, v131, vcc
	v_pk_mul_f32 v[6:7], v[6:7], v[16:17] op_sel_hi:[1,0]
	v_pk_mul_f32 v[4:5], v[4:5], v[16:17] op_sel_hi:[1,0]
	v_pk_mul_f32 v[2:3], v[2:3], v[16:17] op_sel_hi:[1,0]
	v_max_f32_e32 v0, 0, v0
	v_max_f32_e32 v1, 0, v1
	global_store_dwordx4 v[12:13], v[8:11], off
	v_max_f32_e32 v4, 0, v4
	v_max_f32_e32 v5, 0, v5
	v_pk_mul_f32 v[8:9], v[0:1], v[0:1]
	v_max_f32_e32 v0, 0, v6
	v_max_f32_e32 v2, 0, v2
	v_max_f32_e32 v1, 0, v7
	v_max_f32_e32 v3, 0, v3
	v_pk_mul_f32 v[4:5], v[4:5], v[4:5]
	v_pk_mul_f32 v[6:7], v[0:1], v[0:1]
	v_pk_mul_f32 v[10:11], v[2:3], v[2:3]
	v_lshl_add_u64 v[22:23], v[130:131], 0, s[4:5]
	v_cvt_pk_bf16_f32 v0, v4, v5
	v_cvt_pk_bf16_f32 v1, v6, v7
	v_cvt_pk_bf16_f32 v2, v8, v9
	v_cvt_pk_bf16_f32 v3, v10, v11
	global_store_dwordx4 v[22:23], v[0:3], off offset:64
	s_waitcnt vmcnt(0)
	s_sub_i32 s0, s2, s49
	v_mov_b32_e32 v41, v175
	s_cmp_lt_u32 s0, 0x7ffffc00
	s_barrier
	s_cbranch_scc1 .LBB0_786
	s_add_i32 s54, s0, 0x400
	s_ashr_i32 s7, s54, 7
	s_bfe_u32 s8, s0, 0x50002
	s_lshl_b32 s0, s7, 11
	s_lshl_b32 s4, s8, 6
	s_or_b32 s6, s4, s0
	v_ashrrev_i32_e32 v118, 4, v41
	v_add_u32_e32 v10, 0x200, v41
	s_and_b32 s10, s2, 3
	v_lshlrev_b32_e32 v34, 3, v41
	v_add_u32_e32 v0, s6, v118
	s_movk_i32 s9, 0x1600
	v_mov_b64_e32 v[8:9], s[74:75]
	v_ashrrev_i32_e32 v119, 4, v10
	v_and_b32_e32 v2, 0x78, v34
	v_mad_i64_i32 v[0:1], s[4:5], v0, s9, v[8:9]
	s_lshl_b32 s0, s10, 8
	v_add_u32_e32 v10, s6, v119
	v_lshl_add_u64 v[0:1], v[0:1], 0, s[0:1]
	v_lshlrev_b32_e32 v128, 1, v2
	v_mad_i64_i32 v[8:9], s[4:5], v10, s9, v[8:9]
	v_lshl_add_u64 v[24:25], v[0:1], 0, v[128:129]
	v_lshl_add_u64 v[8:9], v[8:9], 0, s[0:1]
	global_load_dwordx4 v[0:3], v[24:25], off offset:1536 nt
	global_load_dwordx4 v[4:7], v[24:25], off offset:2560 nt
	v_lshl_add_u64 v[26:27], v[8:9], 0, v[128:129]
	global_load_dwordx4 v[8:11], v[24:25], off offset:3584 nt
	global_load_dwordx4 v[12:15], v[26:27], off offset:1536 nt
	global_load_dwordx4 v[16:19], v[26:27], off offset:2560 nt
	global_load_dwordx4 v[20:23], v[26:27], off offset:3584 nt
	s_lshl_b32 s0, s7, 5
	s_max_u32 s1, s8, 1
	s_or_b32 s0, s0, s1
	s_add_i32 s0, s0, -1
	s_ashr_i32 s1, s0, 31
	s_lshl_b64 s[0:1], s[0:1], 17
	s_add_u32 s0, s46, s0
	s_addc_u32 s1, s3, s1
	s_lshl_b32 s11, s10, 15
	s_add_u32 s4, s0, s11
	s_addc_u32 s5, s1, 0
	s_cmp_lg_u32 s8, 0
	s_cselect_b64 s[0:1], -1, 0
	v_lshl_add_u64 v[32:33], s[4:5], 0, v[128:129]
	s_and_b64 vcc, exec, s[0:1]
	s_cbranch_vccz .LBB0_833
	v_and_b32_e32 v68, 0xffffff80, v34
	v_add_u32_e32 v24, 0x1000, v68
	v_ashrrev_i32_e32 v69, 31, v68
	v_ashrrev_i32_e32 v25, 31, v24
	v_lshl_add_u64 v[38:39], v[68:69], 1, v[32:33]
	v_lshl_add_u64 v[36:37], v[24:25], 1, v[32:33]
	global_load_dwordx4 v[28:31], v[38:39], off nt
	global_load_dwordx4 v[24:27], v[36:37], off nt
	s_cbranch_execnz .LBB0_765
